# attention loop: 32 exps per half-step re-spaced evenly over the QK MFMA gaps (4 retargeted to free VGPRs), redundant hazard nops dropped
# speedup vs baseline: 1.0155x; 1.0087x over previous
.LBB0_895:
	ds_read_b128 v[124:127], v201 offset:12288
	ds_read_b128 v[128:131], v201 offset:13312
	ds_read_b128 v[136:139], v201 offset:15360
	ds_read_b128 v[140:143], v201 offset:14336
	ds_read_b128 v[148:151], v201 offset:18432
	ds_read_b128 v[152:155], v201 offset:19456
	ds_read_b128 v[204:207], v201 offset:21504
	ds_read_b128 v[208:211], v201 offset:20480
	s_waitcnt lgkmcnt(7)
	v_mfma_f32_16x16x32_bf16 v[132:135], v[124:127], v[12:15], v[44:47]
	v_exp_f32_e32 v195, v84
	v_exp_f32_e32 v194, v88
	v_mfma_f32_16x16x32_bf16 v[124:127], v[124:127], v[16:19], v[48:51]
	v_exp_f32_e32 v88, v91
	v_exp_f32_e32 v84, v81
	s_waitcnt lgkmcnt(3)
	v_mfma_f32_16x16x32_bf16 v[190:193], v[148:151], v[12:15], v[44:47]
	v_exp_f32_e32 v81, v78
	v_exp_f32_e32 v79, v79
	v_mfma_f32_16x16x32_bf16 v[148:151], v[148:151], v[16:19], v[48:51]
	v_exp_f32_e32 v78, v83
	v_exp_f32_e32 v61, v61
	v_mfma_f32_16x16x32_bf16 v[144:147], v[136:139], v[12:15], v[44:47]
	v_exp_f32_e32 v63, v63
	v_exp_f32_e32 v83, v64
	v_mfma_f32_16x16x32_bf16 v[136:139], v[136:139], v[16:19], v[48:51]
	v_exp_f32_e32 v64, v74
	v_exp_f32_e32 v67, v67
	s_waitcnt lgkmcnt(1)
	v_mfma_f32_16x16x32_bf16 v[212:215], v[204:207], v[12:15], v[44:47]
	v_exp_f32_e32 v250, v90
	v_mfma_f32_16x16x32_bf16 v[204:207], v[204:207], v[16:19], v[48:51]
	v_mfma_f32_16x16x32_bf16 v[132:135], v[128:131], v[4:7], v[132:135]
	v_mfma_f32_16x16x32_bf16 v[124:127], v[128:131], v[20:23], v[124:127]
	ds_read_b128 v[128:131], v201 offset:16384
	ds_read_b128 v[216:219], v201 offset:17408
	v_mfma_f32_16x16x32_bf16 v[220:223], v[152:155], v[20:23], v[148:151]
	v_exp_f32_e32 v249, v85
	v_exp_f32_e32 v248, v89
	v_exp_f32_e32 v251, v86
	ds_read_b128 v[148:151], v201 offset:22528
	ds_read_b128 v[224:227], v201 offset:23552
	s_waitcnt lgkmcnt(3)
	v_mfma_f32_16x16x32_bf16 v[144:147], v[128:131], v[4:7], v[144:147]
	v_exp_f32_e32 v89, v87
	v_exp_f32_e32 v87, v76
	v_mfma_f32_16x16x32_bf16 v[128:131], v[128:131], v[20:23], v[136:139]
	v_exp_f32_e32 v86, v80
	s_waitcnt lgkmcnt(1)
	v_mfma_f32_16x16x32_bf16 v[204:207], v[148:151], v[20:23], v[204:207]
	v_exp_f32_e32 v85, v77
	v_exp_f32_e32 v80, v82
	v_mfma_f32_16x16x32_bf16 v[136:139], v[152:155], v[4:7], v[190:193]
	v_exp_f32_e32 v77, v60
	v_mfma_f32_16x16x32_bf16 v[212:215], v[148:151], v[4:7], v[212:215]
	v_exp_f32_e32 v76, v68
	v_exp_f32_e32 v60, v69
	v_mfma_f32_16x16x32_bf16 v[148:151], v[140:143], v[8:11], v[132:135]
	v_exp_f32_e32 v69, v62
	v_mfma_f32_16x16x32_bf16 v[152:155], v[140:143], v[24:27], v[124:127]
	v_exp_f32_e32 v68, v70
	v_exp_f32_e32 v62, v71
	v_mfma_f32_16x16x32_bf16 v[140:143], v[216:219], v[8:11], v[144:147]
	v_exp_f32_e32 v82, v72
	v_mfma_f32_16x16x32_bf16 v[144:147], v[216:219], v[24:27], v[128:131]
	v_exp_f32_e32 v71, v65
	v_exp_f32_e32 v70, v73
	s_waitcnt lgkmcnt(0)
	v_mfma_f32_16x16x32_bf16 v[128:131], v[224:227], v[24:27], v[204:207]
	v_exp_f32_e32 v65, v66
	ds_read_b128 v[204:207], v200 offset:24576
	v_mfma_f32_16x16x32_bf16 v[132:135], v[208:211], v[8:11], v[136:139]
	v_exp_f32_e32 v66, v75
	v_cvt_pk_bf16_f32 v90, v77, v61
	v_mfma_f32_16x16x32_bf16 v[136:139], v[208:211], v[24:27], v[220:223]
	v_cvt_pk_bf16_f32 v208, v195, v249
	v_cvt_pk_bf16_f32 v209, v251, v89
	v_cvt_pk_bf16_f32 v210, v87, v85
	v_mfma_f32_16x16x32_bf16 v[124:127], v[224:227], v[8:11], v[212:215]
	v_cvt_pk_bf16_f32 v211, v81, v79
	ds_read_b128 v[216:219], v200 offset:26624
	ds_read_b128 v[220:223], v200 offset:25600
	v_cvt_pk_bf16_f32 v212, v194, v248
	v_cvt_pk_bf16_f32 v213, v250, v88
	v_cvt_pk_bf16_f32 v214, v86, v84
	v_cvt_pk_bf16_f32 v215, v80, v78
	s_waitcnt lgkmcnt(2)
	v_mfma_f32_16x16x32_bf16 v[120:123], v[204:207], v[208:211], v[120:123]
	v_cvt_pk_bf16_f32 v91, v69, v63
	v_mfma_f32_16x16x32_bf16 v[104:107], v[204:207], v[212:215], v[104:107]
	ds_read_b128 v[204:207], v200 offset:28672
	ds_read_b128 v[224:227], v200 offset:27648
	s_waitcnt lgkmcnt(3)
	v_mfma_f32_16x16x32_bf16 v[228:231], v[216:219], v[208:211], v[116:119]
	v_mfma_f32_16x16x32_bf16 v[100:103], v[216:219], v[212:215], v[100:103]
	s_nop 1
	ds_read_b128 v[116:119], v200 offset:30720
	ds_read_b128 v[216:219], v200 offset:29696
	s_waitcnt lgkmcnt(3)
	v_mfma_f32_16x16x32_bf16 v[232:235], v[204:207], v[208:211], v[112:115]
	v_mfma_f32_16x16x32_bf16 v[96:99], v[204:207], v[212:215], v[96:99]
	ds_read_b128 v[204:207], v200 offset:31744
	s_waitcnt lgkmcnt(2)
	v_mfma_f32_16x16x32_bf16 v[208:211], v[116:119], v[208:211], v[108:111]
	v_mfma_f32_16x16x32_bf16 v[72:75], v[116:119], v[212:215], v[92:95]
	v_cvt_pk_bf16_f32 v212, v76, v60
	v_cvt_pk_bf16_f32 v213, v68, v62
	v_cvt_pk_bf16_f32 v214, v82, v70
	v_cvt_pk_bf16_f32 v92, v83, v71
	v_cvt_pk_bf16_f32 v93, v65, v67
	v_cvt_pk_bf16_f32 v215, v64, v66
	s_nop 0
	v_mfma_f32_16x16x32_bf16 v[120:123], v[220:223], v[90:93], v[120:123]
	v_mfma_f32_16x16x32_bf16 v[116:119], v[220:223], v[212:215], v[104:107]
	v_max3_f32 v244, v152, v153, v154
	v_max3_f32 v245, v148, v149, v150
	v_mfma_f32_16x16x32_bf16 v[112:115], v[224:227], v[90:93], v[228:231]
	v_max3_f32 v244, v244, v155, v144
	v_max3_f32 v245, v245, v151, v140
	v_mfma_f32_16x16x32_bf16 v[108:111], v[224:227], v[212:215], v[100:103]
	v_max3_f32 v244, v244, v145, v146
	v_max3_f32 v245, v245, v141, v142
	s_waitcnt lgkmcnt(1)
	v_mfma_f32_16x16x32_bf16 v[104:107], v[216:219], v[90:93], v[232:235]
	v_max3_f32 v244, v244, v147, v136
	v_max3_f32 v245, v245, v143, v132
	v_mfma_f32_16x16x32_bf16 v[100:103], v[216:219], v[212:215], v[96:99]
	v_max3_f32 v244, v244, v137, v138
	v_max3_f32 v245, v245, v133, v134
	s_waitcnt lgkmcnt(0)
	v_mfma_f32_16x16x32_bf16 v[92:95], v[204:207], v[90:93], v[208:211]
	v_max3_f32 v244, v244, v139, v128
	v_max3_f32 v245, v245, v135, v124
	v_mfma_f32_16x16x32_bf16 v[96:99], v[204:207], v[212:215], v[72:75]
	v_max3_f32 v244, v244, v129, v130
	v_max3_f32 v245, v245, v125, v126
	s_waitcnt vmcnt(0)
	ds_write_b128 v197, v[52:55]
	s_and_saveexec_b64 s[16:17], s[10:11]
	ds_write_b128 v199, v[28:31]
	s_or_b64 exec, exec, s[16:17]

.LBB0_905:
	v_pk_add_f32 v[236:237], v[194:195], v[86:87]
	v_pk_add_f32 v[238:239], v[248:249], v[84:85]
	v_pk_add_f32 v[240:241], v[80:81], v[250:251]
	v_pk_add_f32 v[242:243], v[78:79], v[88:89]
	v_pk_add_f32 v[236:237], v[236:237], v[76:77]
	v_pk_add_f32 v[238:239], v[60:61], v[238:239]
	v_pk_add_f32 v[240:241], v[68:69], v[240:241]
	v_pk_add_f32 v[242:243], v[62:63], v[242:243]
	v_pk_add_f32 v[236:237], v[236:237], v[82:83]
	v_pk_add_f32 v[238:239], v[70:71], v[238:239]
	v_pk_add_f32 v[240:241], v[64:65], v[240:241]
	v_pk_add_f32 v[242:243], v[66:67], v[242:243]
	v_pk_add_f32 v[238:239], v[236:237], v[238:239]
	v_pk_add_f32 v[242:243], v[240:241], v[242:243]
	v_max_f32_e32 v60, v244, v131
	v_pk_add_f32 v[238:239], v[238:239], v[242:243]
	v_max_f32_e32 v61, v245, v127
	v_pk_add_f32 v[184:185], v[184:185], v[238:239]
	v_max_f32_e32 v62, v61, v60
	v_cmp_lt_f32_e32 vcc, s8, v62
	s_cbranch_vccz .LBB0_907
	v_and_b32_e32 v63, 64, v202
	v_xor_b32_e32 v62, 16, v202
	v_add_u32_e32 v63, 64, v63
	v_cmp_lt_i32_e32 vcc, v62, v63
	v_xor_b32_e32 v65, 32, v202
	s_nop 0
	v_cndmask_b32_e32 v62, v202, v62, vcc
	v_lshlrev_b32_e32 v62, 2, v62
	ds_bpermute_b32 v64, v62, v61
	ds_bpermute_b32 v62, v62, v60
	v_cmp_lt_i32_e32 vcc, v65, v63
	v_max_f32_e32 v61, v61, v61
	v_max_f32_e32 v60, v60, v60
	s_waitcnt lgkmcnt(1)
	v_max_f32_e32 v64, v64, v64
	v_cndmask_b32_e32 v63, v202, v65, vcc
	v_max_f32_e32 v61, v61, v64
	v_lshlrev_b32_e32 v63, 2, v63
	s_waitcnt lgkmcnt(0)
	v_max_f32_e32 v62, v62, v62
	ds_bpermute_b32 v64, v63, v61
	v_max_f32_e32 v60, v60, v62
	ds_bpermute_b32 v62, v63, v60
	s_waitcnt lgkmcnt(1)
	v_max_f32_e32 v63, v64, v64
	v_max_f32_e32 v61, v61, v63
	s_waitcnt lgkmcnt(0)
	v_max_f32_e32 v62, v62, v62
	v_max_f32_e32 v60, v60, v62
	v_cmp_lt_f32_e32 vcc, s8, v61
	s_nop 1
	v_cndmask_b32_e32 v61, 0, v61, vcc
	v_cmp_lt_f32_e32 vcc, s8, v60
	v_sub_f32_e32 v148, v148, v61
	v_sub_f32_e32 v149, v149, v61
	v_cndmask_b32_e32 v64, 0, v60, vcc
	v_exp_f32_e64 v60, -v61
	v_exp_f32_e64 v62, -v64
	v_sub_f32_e32 v150, v150, v61
	v_sub_f32_e32 v151, v151, v61
	v_sub_f32_e32 v152, v152, v64
	v_pk_mul_f32 v[118:119], v[118:119], v[62:63] op_sel_hi:[1,0]
	v_pk_mul_f32 v[116:117], v[116:117], v[62:63] op_sel_hi:[1,0]
	v_pk_mul_f32 v[110:111], v[110:111], v[62:63] op_sel_hi:[1,0]
	v_pk_mul_f32 v[108:109], v[108:109], v[62:63] op_sel_hi:[1,0]
	v_pk_mul_f32 v[102:103], v[102:103], v[62:63] op_sel_hi:[1,0]
	v_pk_mul_f32 v[100:101], v[100:101], v[62:63] op_sel_hi:[1,0]
	v_pk_mul_f32 v[98:99], v[98:99], v[62:63] op_sel_hi:[1,0]
	v_pk_mul_f32 v[96:97], v[96:97], v[62:63] op_sel_hi:[1,0]
	v_mov_b32_e32 v63, v60
	v_sub_f32_e32 v153, v153, v64
	v_sub_f32_e32 v154, v154, v64
	v_sub_f32_e32 v155, v155, v64
	v_pk_mul_f32 v[122:123], v[122:123], v[60:61] op_sel_hi:[1,0]
	v_pk_mul_f32 v[120:121], v[120:121], v[60:61] op_sel_hi:[1,0]
	v_sub_f32_e32 v140, v140, v61
	v_sub_f32_e32 v141, v141, v61
	v_sub_f32_e32 v142, v142, v61
	v_sub_f32_e32 v143, v143, v61
	v_sub_f32_e32 v144, v144, v64
	v_sub_f32_e32 v145, v145, v64
	v_sub_f32_e32 v146, v146, v64
	v_sub_f32_e32 v147, v147, v64
	v_pk_mul_f32 v[114:115], v[114:115], v[60:61] op_sel_hi:[1,0]
	v_pk_mul_f32 v[112:113], v[112:113], v[60:61] op_sel_hi:[1,0]
	v_sub_f32_e32 v132, v132, v61
	v_sub_f32_e32 v133, v133, v61
	v_sub_f32_e32 v134, v134, v61
	v_sub_f32_e32 v135, v135, v61
	v_sub_f32_e32 v136, v136, v64
	v_sub_f32_e32 v137, v137, v64
	v_sub_f32_e32 v138, v138, v64
	v_sub_f32_e32 v139, v139, v64
	v_pk_mul_f32 v[106:107], v[106:107], v[60:61] op_sel_hi:[1,0]
	v_pk_mul_f32 v[104:105], v[104:105], v[60:61] op_sel_hi:[1,0]
	v_sub_f32_e32 v124, v124, v61
	v_sub_f32_e32 v125, v125, v61
	v_sub_f32_e32 v126, v126, v61
	v_sub_f32_e32 v127, v127, v61
	v_sub_f32_e32 v128, v128, v64
	v_sub_f32_e32 v129, v129, v64
	v_sub_f32_e32 v130, v130, v64
	v_sub_f32_e32 v131, v131, v64
	v_pk_mul_f32 v[94:95], v[94:95], v[60:61] op_sel_hi:[1,0]
	v_pk_mul_f32 v[92:93], v[92:93], v[60:61] op_sel_hi:[1,0]
	v_pk_mul_f32 v[184:185], v[184:185], v[62:63]
	v_sub_f32_e32 v47, v47, v61
	v_sub_f32_e32 v46, v46, v61
	v_sub_f32_e32 v45, v45, v61
	v_sub_f32_e32 v44, v44, v61
	v_sub_f32_e32 v51, v51, v64
	v_sub_f32_e32 v50, v50, v64
	v_sub_f32_e32 v49, v49, v64
	v_sub_f32_e32 v48, v48, v64
.LBB0_907:
	ds_read_b128 v[60:63], v201
	ds_read_b128 v[64:67], v201 offset:1024
	ds_read_b128 v[72:75], v201 offset:3072
	ds_read_b128 v[76:79], v201 offset:2048
	ds_read_b128 v[84:87], v201 offset:6144
	ds_read_b128 v[88:91], v201 offset:7168
	ds_read_b128 v[190:193], v201 offset:9216
	ds_read_b128 v[204:207], v201 offset:8192
	s_waitcnt lgkmcnt(7)
	v_mfma_f32_16x16x32_bf16 v[68:71], v[60:63], v[12:15], v[44:47]
	v_exp_f32_e32 v149, v149
	v_exp_f32_e32 v151, v151
	v_mfma_f32_16x16x32_bf16 v[60:63], v[60:63], v[16:19], v[48:51]
	v_exp_f32_e32 v143, v143
	v_exp_f32_e32 v133, v133
	s_waitcnt lgkmcnt(3)
	v_mfma_f32_16x16x32_bf16 v[186:189], v[84:87], v[12:15], v[44:47]
	v_exp_f32_e32 v135, v135
	v_exp_f32_e32 v127, v127
	v_mfma_f32_16x16x32_bf16 v[84:87], v[84:87], v[16:19], v[48:51]
	v_exp_f32_e32 v249, v148
	v_exp_f32_e32 v248, v152
	v_mfma_f32_16x16x32_bf16 v[80:83], v[72:75], v[12:15], v[44:47]
	v_exp_f32_e32 v148, v153
	v_mfma_f32_16x16x32_bf16 v[72:75], v[72:75], v[16:19], v[48:51]
	v_exp_f32_e32 v153, v150
	v_exp_f32_e32 v152, v154
	s_waitcnt lgkmcnt(1)
	v_mfma_f32_16x16x32_bf16 v[208:211], v[190:193], v[12:15], v[44:47]
	v_exp_f32_e32 v150, v155
	v_mfma_f32_16x16x32_bf16 v[190:193], v[190:193], v[16:19], v[48:51]
	v_exp_f32_e32 v155, v141
	v_exp_f32_e32 v154, v145
	v_mfma_f32_16x16x32_bf16 v[68:71], v[64:67], v[4:7], v[68:71]
	v_exp_f32_e32 v145, v142
	v_mfma_f32_16x16x32_bf16 v[60:63], v[64:67], v[20:23], v[60:63]
	v_exp_f32_e32 v142, v147
	ds_read_b128 v[64:67], v201 offset:4096
	ds_read_b128 v[212:215], v201 offset:5120
	v_mfma_f32_16x16x32_bf16 v[216:219], v[88:91], v[20:23], v[84:87]
	v_exp_f32_e32 v141, v132
	v_exp_f32_e32 v132, v137
	v_exp_f32_e32 v251, v140
	ds_read_b128 v[84:87], v201 offset:10240
	ds_read_b128 v[220:223], v201 offset:11264
	s_waitcnt lgkmcnt(3)
	v_mfma_f32_16x16x32_bf16 v[80:83], v[64:67], v[4:7], v[80:83]
	v_exp_f32_e32 v250, v144
	v_mfma_f32_16x16x32_bf16 v[64:67], v[64:67], v[20:23], v[72:75]
	v_exp_f32_e32 v144, v146
	v_exp_f32_e32 v140, v136
	v_mfma_f32_16x16x32_bf16 v[72:75], v[88:91], v[4:7], v[186:189]
	v_exp_f32_e32 v137, v134
	s_waitcnt lgkmcnt(1)
	v_mfma_f32_16x16x32_bf16 v[188:191], v[84:87], v[20:23], v[190:193]
	v_exp_f32_e32 v136, v138
	v_exp_f32_e32 v134, v139
	v_mfma_f32_16x16x32_bf16 v[88:91], v[76:79], v[24:27], v[60:63]
	v_exp_f32_e32 v139, v124
	v_mfma_f32_16x16x32_bf16 v[60:63], v[204:207], v[8:11], v[72:75]
	v_exp_f32_e32 v138, v128
	s_waitcnt lgkmcnt(0)
	v_mfma_f32_16x16x32_bf16 v[72:75], v[220:223], v[24:27], v[188:191]
	v_exp_f32_e32 v147, v125
	ds_read_b128 v[190:193], v200 offset:32768
	v_mfma_f32_16x16x32_bf16 v[208:211], v[84:87], v[4:7], v[208:211]
	v_exp_f32_e32 v146, v129
	v_mfma_f32_16x16x32_bf16 v[84:87], v[76:79], v[8:11], v[68:71]
	v_exp_f32_e32 v125, v126
	v_mfma_f32_16x16x32_bf16 v[76:79], v[212:215], v[8:11], v[80:83]
	v_exp_f32_e32 v124, v130
	v_mfma_f32_16x16x32_bf16 v[80:83], v[212:215], v[24:27], v[64:67]
	v_exp_f32_e32 v126, v131
	v_mfma_f32_16x16x32_bf16 v[68:71], v[204:207], v[24:27], v[216:219]
	ds_read_b128 v[212:215], v200 offset:34816
	s_nop 1
	ds_read_b128 v[216:219], v200 offset:33792
	v_cvt_pk_bf16_f32 v204, v249, v149
	v_cvt_pk_bf16_f32 v205, v153, v151
	v_mfma_f32_16x16x32_bf16 v[64:67], v[220:223], v[8:11], v[208:211]
	v_cvt_pk_bf16_f32 v206, v251, v155
	v_cvt_pk_bf16_f32 v207, v145, v143
	v_cvt_pk_bf16_f32 v208, v248, v148
	v_cvt_pk_bf16_f32 v209, v152, v150
	v_cvt_pk_bf16_f32 v210, v250, v154
	v_cvt_pk_bf16_f32 v211, v144, v142
	s_waitcnt lgkmcnt(2)
	v_mfma_f32_16x16x32_bf16 v[120:123], v[190:193], v[204:207], v[120:123]
	v_mfma_f32_16x16x32_bf16 v[116:119], v[190:193], v[208:211], v[116:119]
	ds_read_b128 v[190:193], v200 offset:36864
	ds_read_b128 v[220:223], v200 offset:35840
	s_waitcnt lgkmcnt(3)
	v_mfma_f32_16x16x32_bf16 v[112:115], v[212:215], v[204:207], v[112:115]
	v_mfma_f32_16x16x32_bf16 v[108:111], v[212:215], v[208:211], v[108:111]
	ds_read_b128 v[212:215], v200 offset:38912
	ds_read_b128 v[224:227], v200 offset:37888
	ds_read_b128 v[232:235], v200 offset:39936
	s_waitcnt lgkmcnt(4)
	v_mfma_f32_16x16x32_bf16 v[228:231], v[190:193], v[204:207], v[104:107]
	v_mfma_f32_16x16x32_bf16 v[190:193], v[190:193], v[208:211], v[100:103]
	s_waitcnt lgkmcnt(2)
	v_mfma_f32_16x16x32_bf16 v[92:95], v[212:215], v[204:207], v[92:95]
	v_cvt_pk_bf16_f32 v204, v141, v133
	v_cvt_pk_bf16_f32 v205, v137, v135
	v_cvt_pk_bf16_f32 v206, v139, v147
	v_mfma_f32_16x16x32_bf16 v[128:131], v[212:215], v[208:211], v[96:99]
	v_cvt_pk_bf16_f32 v207, v125, v127
	v_cvt_pk_bf16_f32 v208, v140, v132
	v_cvt_pk_bf16_f32 v209, v136, v134
	v_cvt_pk_bf16_f32 v210, v138, v146
	v_cvt_pk_bf16_f32 v211, v124, v126
	v_mfma_f32_16x16x32_bf16 v[120:123], v[216:219], v[204:207], v[120:123]
	s_nop 0
	v_mfma_f32_16x16x32_bf16 v[104:107], v[216:219], v[208:211], v[116:119]
	v_max3_f32 v246, v88, v89, v90
	v_max3_f32 v247, v84, v85, v86
	v_mfma_f32_16x16x32_bf16 v[116:119], v[220:223], v[204:207], v[112:115]
	v_max3_f32 v246, v246, v91, v80
	v_max3_f32 v247, v247, v87, v76
	v_mfma_f32_16x16x32_bf16 v[100:103], v[220:223], v[208:211], v[108:111]
	v_max3_f32 v246, v246, v81, v82
	v_max3_f32 v247, v247, v77, v78
	s_waitcnt lgkmcnt(1)
	v_mfma_f32_16x16x32_bf16 v[112:115], v[224:227], v[204:207], v[228:231]
	v_max3_f32 v246, v246, v83, v68
	v_max3_f32 v247, v247, v79, v60
	v_mfma_f32_16x16x32_bf16 v[96:99], v[224:227], v[208:211], v[190:193]
	v_max3_f32 v246, v246, v69, v70
	v_max3_f32 v247, v247, v61, v62
	s_waitcnt lgkmcnt(0)
	v_mfma_f32_16x16x32_bf16 v[108:111], v[232:235], v[204:207], v[92:95]
	v_max3_f32 v246, v246, v71, v72
	v_max3_f32 v247, v247, v63, v64
	v_mfma_f32_16x16x32_bf16 v[92:95], v[232:235], v[208:211], v[128:131]
	v_max3_f32 v246, v246, v73, v74
	v_max3_f32 v247, v247, v65, v66
	ds_write_b128 v197, v[32:35] offset:12288
	s_and_saveexec_b64 s[16:17], s[10:11]
	ds_write_b128 v199, v[36:39] offset:12288
	s_or_b64 exec, exec, s[16:17]
.LBB0_911:
	ds_write2_b64 v177, v[40:41], v[42:43] offset1:32
	v_pk_add_f32 v[236:237], v[248:249], v[250:251]
	v_pk_add_f32 v[238:239], v[148:149], v[154:155]
	v_pk_add_f32 v[240:241], v[144:145], v[152:153]
	v_pk_add_f32 v[242:243], v[142:143], v[150:151]
	v_pk_add_f32 v[236:237], v[236:237], v[140:141]
	v_pk_add_f32 v[238:239], v[238:239], v[132:133]
	v_pk_add_f32 v[240:241], v[136:137], v[240:241]
	v_pk_add_f32 v[242:243], v[134:135], v[242:243]
	v_pk_add_f32 v[236:237], v[236:237], v[138:139]
	v_pk_add_f32 v[238:239], v[238:239], v[146:147]
	v_pk_add_f32 v[240:241], v[124:125], v[240:241]
	v_pk_add_f32 v[242:243], v[126:127], v[242:243]
	s_add_i32 s26, s26, 2
	v_pk_add_f32 v[240:241], v[240:241], v[242:243]
	v_pk_add_f32 v[236:237], v[236:237], v[238:239]
	v_lshl_add_u64 v[2:3], v[2:3], 0, s[42:43]
	v_pk_add_f32 v[236:237], v[236:237], v[240:241]
	v_lshl_add_u64 v[180:181], v[180:181], 0, s[44:45]
	v_pk_add_f32 v[184:185], v[184:185], v[236:237]
	v_lshl_add_u64 v[182:183], v[182:183], 0, s[46:47]
	s_cmpk_gt_u32 s26, 0x7f
	s_waitcnt lgkmcnt(0)
	s_barrier
	s_cbranch_scc0 .LBB0_887
	s_waitcnt vmcnt(0)
	s_branch .LBB0_857
